# also nt: bf16 weight stores of the in-loop conversion (read a layer later) and the f32 K/V cache loads of the sample attention units
# speedup vs baseline: 1.0061x; 1.0061x over previous
.LBB0_449:
	s_andn2_saveexec_b64 s[28:29], s[28:29]
	s_cbranch_execz .LBB0_451
	v_ashrrev_i32_e32 v1, 31, v0
	v_lshlrev_b64 v[0:1], 8, v[0:1]
	s_or_b64 s[72:73], s[92:93], s[14:15]
	s_ashr_i32 s11, s10, 31
	v_lshl_add_u64 v[0:1], s[72:73], 0, v[0:1]
	s_lshl_b64 s[42:43], s[10:11], 15
	v_or_b32_e32 v0, v0, v3
	v_lshl_add_u64 v[0:1], v[0:1], 0, s[42:43]
	v_readlane_b32 s56, v253, 42
	v_lshlrev_b64 v[0:1], 2, v[0:1]
	v_readlane_b32 s62, v253, 48
	v_readlane_b32 s63, v253, 49
	v_readlane_b32 s64, v253, 50
	v_readlane_b32 s65, v253, 51
	v_lshl_add_u64 v[10:11], s[62:63], 0, v[0:1]
	global_load_dwordx4 v[6:9], v[10:11], off offset:16 nt
	s_nop 0
	global_load_dwordx4 v[10:13], v[10:11], off nt
	v_lshl_add_u64 v[0:1], s[64:65], 0, v[0:1]
	global_load_dwordx4 v[14:17], v[0:1], off offset:16 nt
	global_load_dwordx4 v[18:21], v[0:1], off nt
	v_readlane_b32 s57, v253, 43
	v_readlane_b32 s58, v253, 44
	v_readlane_b32 s59, v253, 45
	v_readlane_b32 s60, v253, 46
	v_readlane_b32 s61, v253, 47
	v_readlane_b32 s66, v253, 52
	v_readlane_b32 s67, v253, 53
	v_readlane_b32 s68, v253, 54
	v_readlane_b32 s69, v253, 55
	v_readlane_b32 s70, v253, 56
	v_readlane_b32 s71, v253, 57
	s_waitcnt vmcnt(3)
	v_cvt_pk_bf16_f32 v82, v6, v7
	s_waitcnt vmcnt(2)
	v_cvt_pk_bf16_f32 v80, v10, v11
	v_cvt_pk_bf16_f32 v81, v12, v13
	v_cvt_pk_bf16_f32 v83, v8, v9
	s_waitcnt vmcnt(1)
	v_cvt_pk_bf16_f32 v94, v14, v15
	s_waitcnt vmcnt(0)
	v_cvt_pk_bf16_f32 v92, v18, v19
	v_cvt_pk_bf16_f32 v93, v20, v21
	v_cvt_pk_bf16_f32 v95, v16, v17

.LBB0_455:
	s_andn2_saveexec_b64 s[28:29], s[28:29]
	s_cbranch_execz .LBB0_457
	v_ashrrev_i32_e32 v1, 31, v0
	v_mov_b32_e32 v5, s35
	s_ashr_i32 s11, s10, 31
	v_lshlrev_b64 v[0:1], 8, v[0:1]
	v_or3_b32 v202, s14, v5, v3
	s_lshl_b64 s[42:43], s[10:11], 15
	v_lshl_add_u64 v[0:1], v[202:203], 0, v[0:1]
	v_lshl_add_u64 v[0:1], v[0:1], 0, s[42:43]
	v_readlane_b32 s56, v253, 42
	v_lshlrev_b64 v[0:1], 2, v[0:1]
	v_readlane_b32 s62, v253, 48
	v_readlane_b32 s63, v253, 49
	v_readlane_b32 s64, v253, 50
	v_readlane_b32 s65, v253, 51
	v_lshl_add_u64 v[10:11], s[62:63], 0, v[0:1]
	global_load_dwordx4 v[6:9], v[10:11], off offset:16 nt
	s_nop 0
	global_load_dwordx4 v[10:13], v[10:11], off nt
	v_lshl_add_u64 v[0:1], s[64:65], 0, v[0:1]
	global_load_dwordx4 v[14:17], v[0:1], off offset:16 nt
	global_load_dwordx4 v[18:21], v[0:1], off nt
	v_readlane_b32 s57, v253, 43
	v_readlane_b32 s58, v253, 44
	v_readlane_b32 s59, v253, 45
	v_readlane_b32 s60, v253, 46
	v_readlane_b32 s61, v253, 47
	v_readlane_b32 s66, v253, 52
	v_readlane_b32 s67, v253, 53
	v_readlane_b32 s68, v253, 54
	v_readlane_b32 s69, v253, 55
	v_readlane_b32 s70, v253, 56
	v_readlane_b32 s71, v253, 57
	s_waitcnt vmcnt(3)
	v_cvt_pk_bf16_f32 v90, v6, v7
	s_waitcnt vmcnt(2)
	v_cvt_pk_bf16_f32 v88, v10, v11
	v_cvt_pk_bf16_f32 v89, v12, v13
	v_cvt_pk_bf16_f32 v91, v8, v9
	s_waitcnt vmcnt(1)
	v_cvt_pk_bf16_f32 v98, v14, v15
	s_waitcnt vmcnt(0)
	v_cvt_pk_bf16_f32 v96, v18, v19
	v_cvt_pk_bf16_f32 v97, v20, v21
	v_cvt_pk_bf16_f32 v99, v16, v17

.LBB0_461:
	s_andn2_saveexec_b64 s[22:23], s[22:23]
	s_cbranch_execz .LBB0_463
	v_ashrrev_i32_e32 v1, 31, v0
	v_mov_b32_e32 v4, s28
	s_ashr_i32 s11, s10, 31
	v_lshlrev_b64 v[0:1], 8, v[0:1]
	v_or3_b32 v202, s14, v4, v3
	s_lshl_b64 s[10:11], s[10:11], 15
	v_lshl_add_u64 v[0:1], v[202:203], 0, v[0:1]
	v_lshl_add_u64 v[0:1], v[0:1], 0, s[10:11]
	v_readlane_b32 s56, v253, 42
	v_lshlrev_b64 v[0:1], 2, v[0:1]
	v_readlane_b32 s62, v253, 48
	v_readlane_b32 s63, v253, 49
	v_readlane_b32 s64, v253, 50
	v_readlane_b32 s65, v253, 51
	v_lshl_add_u64 v[8:9], s[62:63], 0, v[0:1]
	global_load_dwordx4 v[4:7], v[8:9], off offset:16 nt
	s_nop 0
	global_load_dwordx4 v[8:11], v[8:9], off nt
	v_lshl_add_u64 v[0:1], s[64:65], 0, v[0:1]
	v_readlane_b32 s57, v253, 43
	v_readlane_b32 s58, v253, 44
	v_readlane_b32 s59, v253, 45
	v_readlane_b32 s60, v253, 46
	v_readlane_b32 s61, v253, 47
	v_readlane_b32 s66, v253, 52
	v_readlane_b32 s67, v253, 53
	v_readlane_b32 s68, v253, 54
	v_readlane_b32 s69, v253, 55
	v_readlane_b32 s70, v253, 56
	v_readlane_b32 s71, v253, 57
	s_waitcnt vmcnt(1)
	v_cvt_pk_bf16_f32 v86, v4, v5
	s_waitcnt vmcnt(0)
	v_cvt_pk_bf16_f32 v84, v8, v9
	v_cvt_pk_bf16_f32 v85, v10, v11
	v_cvt_pk_bf16_f32 v87, v6, v7
	global_load_dwordx4 v[4:7], v[0:1], off offset:16 nt
	global_load_dwordx4 v[8:11], v[0:1], off nt
	s_waitcnt vmcnt(1)
	v_cvt_pk_bf16_f32 v102, v4, v5
	s_waitcnt vmcnt(0)
	v_cvt_pk_bf16_f32 v100, v8, v9
	v_cvt_pk_bf16_f32 v101, v10, v11
	v_cvt_pk_bf16_f32 v103, v6, v7

.LBB0_793:
	v_add_u32_e32 v4, 0x1ce0, v14
	s_waitcnt vmcnt(0)
	ds_write2_b32 v4, v0, v1 offset1:1
	v_add_u32_e32 v0, 0x1ce8, v14
	ds_write2_b32 v0, v2, v3 offset1:1
	v_lshlrev_b32_e32 v0, 3, v12
	v_and_b32_e32 v0, 56, v0
	v_mul_u32_u24_e32 v1, 0x84, v0
	v_lshlrev_b32_e32 v194, 1, v0
	v_lshlrev_b32_e32 v0, 2, v10
	s_waitcnt lgkmcnt(0)
	v_add3_u32 v30, s33, v1, v0
	s_ashr_i32 s15, s14, 31
	ds_read2_b32 v[6:7], v30 offset0:33 offset1:41
	ds_read2_b32 v[14:15], v30 offset1:8
	ds_read2_b32 v[16:17], v30 offset0:66 offset1:74
	ds_read2_b32 v[18:19], v30 offset0:99 offset1:107
	ds_read2_b32 v[20:21], v30 offset0:132 offset1:140
	ds_read2_b32 v[22:23], v30 offset0:165 offset1:173
	ds_read2_b32 v[24:25], v30 offset0:198 offset1:206
	ds_read2_b32 v[26:27], v30 offset0:231 offset1:239
	s_lshl_b64 s[0:1], s[14:15], 1
	s_add_u32 s0, s6, s0
	v_add_u32_e32 v28, s3, v10
	s_addc_u32 s1, s7, s1
	v_ashrrev_i32_e32 v29, 31, v28
	v_lshl_add_u64 v[4:5], s[0:1], 0, v[194:195]
	v_lshlrev_b64 v[28:29], 11, v[28:29]
	s_waitcnt lgkmcnt(6)
	v_cvt_pk_bf16_f32 v0, v14, v6
	s_waitcnt lgkmcnt(4)
	v_cvt_pk_bf16_f32 v1, v16, v18
	s_waitcnt lgkmcnt(2)
	v_cvt_pk_bf16_f32 v2, v20, v22
	s_waitcnt lgkmcnt(0)
	v_cvt_pk_bf16_f32 v3, v24, v26
	v_lshl_add_u64 v[28:29], v[4:5], 0, v[28:29]
	v_add_u32_e32 v6, s3, v9
	global_store_dwordx4 v[28:29], v[0:3], off nt
	v_add_u32_e32 v10, s3, v11
	v_ashrrev_i32_e32 v11, 31, v10
	v_cvt_pk_bf16_f32 v0, v15, v7
	v_ashrrev_i32_e32 v7, 31, v6
	v_lshlrev_b64 v[6:7], 11, v[6:7]
	v_cvt_pk_bf16_f32 v1, v17, v19
	v_cvt_pk_bf16_f32 v2, v21, v23
	v_cvt_pk_bf16_f32 v3, v25, v27
	v_lshl_add_u64 v[6:7], v[4:5], 0, v[6:7]
	global_store_dwordx4 v[6:7], v[0:3], off nt
	ds_read2_b32 v[6:7], v30 offset0:49 offset1:57
	ds_read2_b32 v[8:9], v30 offset0:16 offset1:24
	ds_read2_b32 v[14:15], v30 offset0:82 offset1:90
	ds_read2_b32 v[16:17], v30 offset0:115 offset1:123
	ds_read2_b32 v[18:19], v30 offset0:148 offset1:156
	ds_read2_b32 v[20:21], v30 offset0:181 offset1:189
	ds_read2_b32 v[22:23], v30 offset0:214 offset1:222
	ds_read2_b32 v[24:25], v30 offset0:247 offset1:255
	v_lshlrev_b64 v[10:11], 11, v[10:11]
	s_waitcnt lgkmcnt(6)
	v_cvt_pk_bf16_f32 v0, v8, v6
	s_waitcnt lgkmcnt(4)
	v_cvt_pk_bf16_f32 v1, v14, v16
	s_waitcnt lgkmcnt(2)
	v_cvt_pk_bf16_f32 v2, v18, v20
	s_waitcnt lgkmcnt(0)
	v_cvt_pk_bf16_f32 v3, v22, v24
	v_lshl_add_u64 v[10:11], v[4:5], 0, v[10:11]
	v_add_u32_e32 v6, s3, v13
	global_store_dwordx4 v[10:11], v[0:3], off nt
	s_nop 1
	v_cvt_pk_bf16_f32 v0, v9, v7
	v_ashrrev_i32_e32 v7, 31, v6
	v_lshlrev_b64 v[6:7], 11, v[6:7]
	v_cvt_pk_bf16_f32 v1, v15, v17
	v_cvt_pk_bf16_f32 v2, v19, v21
	v_cvt_pk_bf16_f32 v3, v23, v25
	v_lshl_add_u64 v[4:5], v[4:5], 0, v[6:7]
	global_store_dwordx4 v[4:5], v[0:3], off nt
	s_waitcnt lgkmcnt(0)

.LBB0_795:
	s_cmpk_gt_i32 s29, 0xcff
	s_mov_b64 s[0:1], -1
	s_cbranch_scc0 .LBB0_853
	s_cmpk_gt_u32 s29, 0xeff
	s_cbranch_scc0 .LBB0_850
	s_cmpk_gt_u32 s29, 0x10ff
	s_cbranch_scc0 .LBB0_847
	s_cmpk_gt_u32 s29, 0x12ff
	s_cbranch_scc0 .LBB0_844
	s_cmpk_gt_u32 s29, 0x137f
	s_cbranch_scc0 .LBB0_825
	s_cmpk_gt_u32 s29, 0x13ff
	s_cbranch_scc0 .LBB0_822
	v_lshlrev_b32_e32 v0, 2, v12
	v_ashrrev_i32_e32 v15, 3, v12
	v_and_b32_e32 v0, 28, v0
	s_cmpk_gt_u32 s29, 0x1bff
	v_lshl_add_u32 v4, v0, 2, s33
	v_add_u32_e32 v14, 8, v15
	v_add_u32_e32 v13, 16, v15
	v_add_u32_e32 v5, 24, v15
	v_lshlrev_b32_e32 v16, 2, v15
	v_lshlrev_b32_e32 v194, 2, v0
	s_cbranch_scc0 .LBB0_803
	s_and_b32 s0, s55, 0x3e0
	s_and_b32 s1, s25, 0x1ffc0
	s_lshl_b32 s3, s0, 2
	v_readlane_b32 s14, v255, 51
	s_add_u32 s14, s14, s3
	v_readlane_b32 s3, v255, 52
	v_add_u32_e32 v8, s1, v15
	s_addc_u32 s15, s3, 0
	v_ashrrev_i32_e32 v9, 31, v8
	v_lshl_add_u64 v[6:7], s[14:15], 0, v[194:195]
	v_lshlrev_b64 v[0:1], 12, v[8:9]
	v_lshl_add_u64 v[0:1], v[6:7], 0, v[0:1]
	global_load_dwordx4 v[0:3], v[0:1], off nt
	v_mad_u64_u32 v[10:11], s[14:15], v15, s49, v[4:5]
	v_add_u32_e32 v9, 0x420, v10
	v_add_u32_e32 v30, s0, v15
	v_ashrrev_i32_e32 v31, 31, v30
	v_lshlrev_b64 v[30:31], 13, v[30:31]
	s_waitcnt vmcnt(0)
	ds_write2_b32 v10, v0, v1 offset1:1
	ds_write2_b32 v10, v2, v3 offset0:2 offset1:3
	v_add_u32_e32 v0, s1, v14
	v_ashrrev_i32_e32 v1, 31, v0
	v_lshlrev_b64 v[0:1], 12, v[0:1]
	v_lshl_add_u64 v[0:1], v[6:7], 0, v[0:1]
	global_load_dwordx4 v[0:3], v[0:1], off nt
	s_waitcnt vmcnt(0)
	ds_write2_b32 v9, v0, v1 offset1:1
	v_add_u32_e32 v0, 0x428, v10
	ds_write2_b32 v0, v2, v3 offset1:1
	v_add_u32_e32 v0, s1, v13
	v_ashrrev_i32_e32 v1, 31, v0
	v_lshlrev_b64 v[0:1], 12, v[0:1]
	v_lshl_add_u64 v[0:1], v[6:7], 0, v[0:1]
	global_load_dwordx4 v[0:3], v[0:1], off nt
	v_add_u32_e32 v9, 0x840, v10
	s_waitcnt vmcnt(0)
	ds_write2_b32 v9, v0, v1 offset1:1
	v_add_u32_e32 v0, 0x848, v10
	ds_write2_b32 v0, v2, v3 offset1:1
	v_add_u32_e32 v0, s1, v5
	v_ashrrev_i32_e32 v1, 31, v0
	v_lshlrev_b64 v[0:1], 12, v[0:1]
	v_lshl_add_u64 v[0:1], v[6:7], 0, v[0:1]
	global_load_dwordx4 v[0:3], v[0:1], off nt
	v_add_u32_e32 v9, 0xc60, v10
	s_lshl_b32 s1, s1, 1
	s_add_u32 s14, s65, s1
	s_addc_u32 s15, s67, 0
	s_waitcnt vmcnt(0)
	ds_write2_b32 v9, v0, v1 offset1:1
	v_add_u32_e32 v0, 0xc68, v10
	ds_write2_b32 v0, v2, v3 offset1:1
	v_add_u32_e32 v0, 32, v8
	v_ashrrev_i32_e32 v1, 31, v0
	v_lshlrev_b64 v[0:1], 12, v[0:1]
	v_lshl_add_u64 v[0:1], v[6:7], 0, v[0:1]
	global_load_dwordx4 v[0:3], v[0:1], off nt
	v_add_u32_e32 v9, 0x1080, v10
	s_waitcnt vmcnt(0)
	ds_write2_b32 v9, v0, v1 offset1:1
	v_add_u32_e32 v0, 0x1088, v10
	ds_write2_b32 v0, v2, v3 offset1:1
	v_add_u32_e32 v0, 40, v8
	v_ashrrev_i32_e32 v1, 31, v0
	v_lshlrev_b64 v[0:1], 12, v[0:1]
	v_lshl_add_u64 v[0:1], v[6:7], 0, v[0:1]
	global_load_dwordx4 v[0:3], v[0:1], off nt
	v_add_u32_e32 v9, 0x14a0, v10
	s_waitcnt vmcnt(0)
	ds_write2_b32 v9, v0, v1 offset1:1
	v_add_u32_e32 v0, 0x14a8, v10
	ds_write2_b32 v0, v2, v3 offset1:1
	v_add_u32_e32 v0, 48, v8
	v_ashrrev_i32_e32 v1, 31, v0
	v_lshlrev_b64 v[0:1], 12, v[0:1]
	v_lshl_add_u64 v[0:1], v[6:7], 0, v[0:1]
	global_load_dwordx4 v[0:3], v[0:1], off nt
	v_add_u32_e32 v9, 0x18c0, v10
	s_waitcnt vmcnt(0)
	ds_write2_b32 v9, v0, v1 offset1:1
	v_add_u32_e32 v0, 0x18c8, v10
	ds_write2_b32 v0, v2, v3 offset1:1
	v_add_u32_e32 v0, 56, v8
	v_ashrrev_i32_e32 v1, 31, v0
	v_lshlrev_b64 v[0:1], 12, v[0:1]
	v_lshl_add_u64 v[0:1], v[6:7], 0, v[0:1]
	global_load_dwordx4 v[0:3], v[0:1], off nt
	v_add_u32_e32 v6, 0x1ce0, v10
	s_waitcnt vmcnt(0)
	ds_write2_b32 v6, v0, v1 offset1:1
	v_add_u32_e32 v0, 0x1ce8, v10
	ds_write2_b32 v0, v2, v3 offset1:1
	v_lshlrev_b32_e32 v0, 3, v12
	v_and_b32_e32 v0, 56, v0
	v_mul_u32_u24_e32 v2, 0x84, v0
	s_waitcnt lgkmcnt(0)
	v_add3_u32 v17, s33, v2, v16
	ds_read2_b32 v[2:3], v17 offset0:33 offset1:41
	ds_read2_b32 v[10:11], v17 offset1:8
	ds_read2_b32 v[18:19], v17 offset0:66 offset1:74
	ds_read2_b32 v[20:21], v17 offset0:99 offset1:107
	ds_read2_b32 v[22:23], v17 offset0:132 offset1:140
	ds_read2_b32 v[24:25], v17 offset0:165 offset1:173
	ds_read2_b32 v[26:27], v17 offset0:198 offset1:206
	ds_read2_b32 v[28:29], v17 offset0:231 offset1:239
	v_lshlrev_b32_e32 v0, 1, v0
	v_mov_b32_e32 v1, v195
	v_lshl_add_u64 v[0:1], s[14:15], 0, v[0:1]
	s_waitcnt lgkmcnt(6)
	v_cvt_pk_bf16_f32 v6, v10, v2
	s_waitcnt lgkmcnt(4)
	v_cvt_pk_bf16_f32 v7, v18, v20
	s_waitcnt lgkmcnt(2)
	v_cvt_pk_bf16_f32 v8, v22, v24
	s_waitcnt lgkmcnt(0)
	v_cvt_pk_bf16_f32 v9, v26, v28
	v_lshl_add_u64 v[30:31], v[0:1], 0, v[30:31]
	v_add_u32_e32 v2, s0, v14
	global_store_dwordx4 v[30:31], v[6:9], off nt
	v_add_u32_e32 v30, s0, v13
	v_ashrrev_i32_e32 v31, 31, v30
	v_cvt_pk_bf16_f32 v6, v11, v3
	v_ashrrev_i32_e32 v3, 31, v2
	v_lshlrev_b64 v[2:3], 13, v[2:3]
	v_cvt_pk_bf16_f32 v7, v19, v21
	v_cvt_pk_bf16_f32 v8, v23, v25
	v_cvt_pk_bf16_f32 v9, v27, v29
	v_lshl_add_u64 v[2:3], v[0:1], 0, v[2:3]
	global_store_dwordx4 v[2:3], v[6:9], off nt
	ds_read2_b32 v[2:3], v17 offset0:49 offset1:57
	ds_read2_b32 v[10:11], v17 offset0:16 offset1:24
	ds_read2_b32 v[18:19], v17 offset0:82 offset1:90
	ds_read2_b32 v[20:21], v17 offset0:115 offset1:123
	ds_read2_b32 v[22:23], v17 offset0:148 offset1:156
	ds_read2_b32 v[24:25], v17 offset0:181 offset1:189
	ds_read2_b32 v[26:27], v17 offset0:214 offset1:222
	ds_read2_b32 v[28:29], v17 offset0:247 offset1:255
	v_lshlrev_b64 v[30:31], 13, v[30:31]
	s_waitcnt lgkmcnt(6)
	v_cvt_pk_bf16_f32 v6, v10, v2
	s_waitcnt lgkmcnt(4)
	v_cvt_pk_bf16_f32 v7, v18, v20
	s_waitcnt lgkmcnt(2)
	v_cvt_pk_bf16_f32 v8, v22, v24
	s_waitcnt lgkmcnt(0)
	v_cvt_pk_bf16_f32 v9, v26, v28
	v_lshl_add_u64 v[30:31], v[0:1], 0, v[30:31]
	v_add_u32_e32 v2, s0, v5
	global_store_dwordx4 v[30:31], v[6:9], off nt
	s_mov_b64 s[0:1], 0
	s_nop 0
	v_cvt_pk_bf16_f32 v6, v11, v3
	v_ashrrev_i32_e32 v3, 31, v2
	v_lshlrev_b64 v[2:3], 13, v[2:3]
	v_cvt_pk_bf16_f32 v7, v19, v21
	v_cvt_pk_bf16_f32 v8, v23, v25
	v_cvt_pk_bf16_f32 v9, v27, v29
	v_lshl_add_u64 v[0:1], v[0:1], 0, v[2:3]
	global_store_dwordx4 v[0:1], v[6:9], off nt
	s_waitcnt lgkmcnt(0)

.LBB0_820:
	v_add_u32_e32 v6, 0x1ce0, v4
	s_waitcnt vmcnt(0)
	ds_write2_b32 v6, v0, v1 offset1:1
	v_add_u32_e32 v0, 0x1ce8, v4
	ds_write2_b32 v0, v2, v3 offset1:1
	v_lshlrev_b32_e32 v0, 3, v12
	v_and_b32_e32 v0, 56, v0
	v_mul_u32_u24_e32 v1, 0x84, v0
	s_waitcnt lgkmcnt(0)
	v_add3_u32 v4, s33, v1, v16
	ds_read2_b32 v[8:9], v4 offset0:33 offset1:41
	ds_read2_b32 v[10:11], v4 offset1:8
	ds_read2_b32 v[16:17], v4 offset0:66 offset1:74
	ds_read2_b32 v[18:19], v4 offset0:99 offset1:107
	ds_read2_b32 v[20:21], v4 offset0:132 offset1:140
	ds_read2_b32 v[22:23], v4 offset0:165 offset1:173
	ds_read2_b32 v[24:25], v4 offset0:198 offset1:206
	ds_read2_b32 v[26:27], v4 offset0:231 offset1:239
	s_lshl_b32 s0, s14, 1
	s_add_u32 s0, s72, s0
	v_add_u32_e32 v28, s3, v15
	s_addc_u32 s1, s73, 0
	v_lshlrev_b32_e32 v194, 1, v0
	v_ashrrev_i32_e32 v29, 31, v28
	v_lshl_add_u64 v[6:7], s[0:1], 0, v[194:195]
	v_lshlrev_b64 v[28:29], 11, v[28:29]
	s_waitcnt lgkmcnt(6)
	v_cvt_pk_bf16_f32 v0, v10, v8
	s_waitcnt lgkmcnt(4)
	v_cvt_pk_bf16_f32 v1, v16, v18
	s_waitcnt lgkmcnt(2)
	v_cvt_pk_bf16_f32 v2, v20, v22
	s_waitcnt lgkmcnt(0)
	v_cvt_pk_bf16_f32 v3, v24, v26
	v_lshl_add_u64 v[28:29], v[6:7], 0, v[28:29]
	v_add_u32_e32 v8, s3, v14
	global_store_dwordx4 v[28:29], v[0:3], off nt
	v_add_u32_e32 v26, s3, v13
	s_nop 0
	v_cvt_pk_bf16_f32 v0, v11, v9
	v_ashrrev_i32_e32 v9, 31, v8
	v_lshlrev_b64 v[8:9], 11, v[8:9]
	v_cvt_pk_bf16_f32 v1, v17, v19
	v_cvt_pk_bf16_f32 v2, v21, v23
	v_cvt_pk_bf16_f32 v3, v25, v27
	v_lshl_add_u64 v[8:9], v[6:7], 0, v[8:9]
	global_store_dwordx4 v[8:9], v[0:3], off nt
	ds_read2_b32 v[8:9], v4 offset0:49 offset1:57
	ds_read2_b32 v[10:11], v4 offset0:16 offset1:24
	ds_read2_b32 v[14:15], v4 offset0:82 offset1:90
	ds_read2_b32 v[16:17], v4 offset0:115 offset1:123
	ds_read2_b32 v[18:19], v4 offset0:148 offset1:156
	ds_read2_b32 v[20:21], v4 offset0:181 offset1:189
	ds_read2_b32 v[22:23], v4 offset0:214 offset1:222
	ds_read2_b32 v[24:25], v4 offset0:247 offset1:255
	v_ashrrev_i32_e32 v27, 31, v26
	v_add_u32_e32 v4, s3, v5
	v_lshlrev_b64 v[26:27], 11, v[26:27]
	v_ashrrev_i32_e32 v5, 31, v4
	s_waitcnt lgkmcnt(6)
	v_cvt_pk_bf16_f32 v0, v10, v8
	s_waitcnt lgkmcnt(4)
	v_cvt_pk_bf16_f32 v1, v14, v16
	s_waitcnt lgkmcnt(2)
	v_cvt_pk_bf16_f32 v2, v18, v20
	s_waitcnt lgkmcnt(0)
	v_cvt_pk_bf16_f32 v3, v22, v24
	v_lshl_add_u64 v[26:27], v[6:7], 0, v[26:27]
	v_lshlrev_b64 v[4:5], 11, v[4:5]
	global_store_dwordx4 v[26:27], v[0:3], off nt
	v_lshl_add_u64 v[4:5], v[6:7], 0, v[4:5]
	s_nop 0
	v_cvt_pk_bf16_f32 v0, v11, v9
	v_cvt_pk_bf16_f32 v1, v15, v17
	v_cvt_pk_bf16_f32 v2, v19, v21
	v_cvt_pk_bf16_f32 v3, v23, v25
	global_store_dwordx4 v[4:5], v[0:3], off nt
	s_waitcnt lgkmcnt(0)

.LBB0_822:
	s_andn2_b64 vcc, exec, s[0:1]
	s_cbranch_vccnz .LBB0_824
	s_add_i32 s0, s25, 0xfffe3800
	s_and_b32 s0, s0, 0x1c0
	s_xor_b32 s1, s0, 0x100
	s_and_b32 s0, s55, 0x3e0
	v_ashrrev_i32_e32 v13, 3, v12
	s_lshl_b32 s3, s0, 2
	v_readlane_b32 s14, v255, 55
	s_add_u32 s14, s14, s3
	v_readlane_b32 s3, v255, 56
	v_lshlrev_b32_e32 v0, 4, v12
	v_add_u32_e32 v6, s1, v13
	s_addc_u32 s15, s3, 0
	v_and_b32_e32 v194, 0x70, v0
	v_ashrrev_i32_e32 v7, 31, v6
	v_lshl_add_u64 v[4:5], s[14:15], 0, v[194:195]
	v_lshlrev_b64 v[0:1], 12, v[6:7]
	v_lshl_add_u64 v[0:1], v[4:5], 0, v[0:1]
	global_load_dwordx4 v[0:3], v[0:1], off nt
	v_mul_lo_u32 v7, v13, s49
	v_add3_u32 v7, s33, v194, v7
	v_add_u32_e32 v26, 8, v13
	v_add_u32_e32 v8, 0x420, v7
	v_add_u32_e32 v27, 16, v13
	v_add_u32_e32 v28, 24, v13
	v_add_u32_e32 v24, s0, v13
	v_ashrrev_i32_e32 v25, 31, v24
	v_lshlrev_b64 v[24:25], 9, v[24:25]
	s_waitcnt vmcnt(0)
	ds_write2_b32 v7, v0, v1 offset1:1
	ds_write2_b32 v7, v2, v3 offset0:2 offset1:3
	v_add_u32_e32 v0, s1, v26
	v_ashrrev_i32_e32 v1, 31, v0
	v_lshlrev_b64 v[0:1], 12, v[0:1]
	v_lshl_add_u64 v[0:1], v[4:5], 0, v[0:1]
	global_load_dwordx4 v[0:3], v[0:1], off nt
	s_waitcnt vmcnt(0)
	ds_write2_b32 v8, v0, v1 offset1:1
	v_add_u32_e32 v0, 0x428, v7
	ds_write2_b32 v0, v2, v3 offset1:1
	v_add_u32_e32 v0, s1, v27
	v_ashrrev_i32_e32 v1, 31, v0
	v_lshlrev_b64 v[0:1], 12, v[0:1]
	v_lshl_add_u64 v[0:1], v[4:5], 0, v[0:1]
	global_load_dwordx4 v[0:3], v[0:1], off nt
	v_add_u32_e32 v8, 0x840, v7
	s_waitcnt vmcnt(0)
	ds_write2_b32 v8, v0, v1 offset1:1
	v_add_u32_e32 v0, 0x848, v7
	ds_write2_b32 v0, v2, v3 offset1:1
	v_add_u32_e32 v0, s1, v28
	v_ashrrev_i32_e32 v1, 31, v0
	v_lshlrev_b64 v[0:1], 12, v[0:1]
	v_lshl_add_u64 v[0:1], v[4:5], 0, v[0:1]
	global_load_dwordx4 v[0:3], v[0:1], off nt
	v_add_u32_e32 v8, 0xc60, v7
	s_lshl_b32 s1, s1, 1
	s_add_u32 s14, s82, s1
	v_readlane_b32 s1, v255, 48
	s_addc_u32 s15, s1, 0
	s_waitcnt vmcnt(0)
	ds_write2_b32 v8, v0, v1 offset1:1
	v_add_u32_e32 v0, 0xc68, v7
	ds_write2_b32 v0, v2, v3 offset1:1
	v_add_u32_e32 v0, 32, v6
	v_ashrrev_i32_e32 v1, 31, v0
	v_lshlrev_b64 v[0:1], 12, v[0:1]
	v_lshl_add_u64 v[0:1], v[4:5], 0, v[0:1]
	global_load_dwordx4 v[0:3], v[0:1], off nt
	v_add_u32_e32 v8, 0x1080, v7
	s_waitcnt vmcnt(0)
	ds_write2_b32 v8, v0, v1 offset1:1
	v_add_u32_e32 v0, 0x1088, v7
	ds_write2_b32 v0, v2, v3 offset1:1
	v_add_u32_e32 v0, 40, v6
	v_ashrrev_i32_e32 v1, 31, v0
	v_lshlrev_b64 v[0:1], 12, v[0:1]
	v_lshl_add_u64 v[0:1], v[4:5], 0, v[0:1]
	global_load_dwordx4 v[0:3], v[0:1], off nt
	v_add_u32_e32 v8, 0x14a0, v7
	s_waitcnt vmcnt(0)
	ds_write2_b32 v8, v0, v1 offset1:1
	v_add_u32_e32 v0, 0x14a8, v7
	ds_write2_b32 v0, v2, v3 offset1:1
	v_add_u32_e32 v0, 48, v6
	v_ashrrev_i32_e32 v1, 31, v0
	v_lshlrev_b64 v[0:1], 12, v[0:1]
	v_lshl_add_u64 v[0:1], v[4:5], 0, v[0:1]
	global_load_dwordx4 v[0:3], v[0:1], off nt
	v_add_u32_e32 v8, 0x18c0, v7
	s_waitcnt vmcnt(0)
	ds_write2_b32 v8, v0, v1 offset1:1
	v_add_u32_e32 v0, 0x18c8, v7
	ds_write2_b32 v0, v2, v3 offset1:1
	v_add_u32_e32 v0, 56, v6
	v_ashrrev_i32_e32 v1, 31, v0
	v_lshlrev_b64 v[0:1], 12, v[0:1]
	v_lshl_add_u64 v[0:1], v[4:5], 0, v[0:1]
	global_load_dwordx4 v[0:3], v[0:1], off nt
	v_add_u32_e32 v4, 0x1ce0, v7
	s_waitcnt vmcnt(0)
	ds_write2_b32 v4, v0, v1 offset1:1
	v_add_u32_e32 v0, 0x1ce8, v7
	ds_write2_b32 v0, v2, v3 offset1:1
	v_lshlrev_b32_e32 v0, 3, v12
	v_and_b32_e32 v0, 56, v0
	v_mul_u32_u24_e32 v1, 0x84, v0
	v_lshlrev_b32_e32 v194, 1, v0
	v_lshlrev_b32_e32 v0, 2, v13
	s_waitcnt lgkmcnt(0)
	v_add3_u32 v29, s33, v1, v0
	ds_read2_b32 v[6:7], v29 offset0:33 offset1:41
	ds_read2_b32 v[8:9], v29 offset1:8
	ds_read2_b32 v[10:11], v29 offset0:66 offset1:74
	ds_read2_b32 v[14:15], v29 offset0:99 offset1:107
	ds_read2_b32 v[16:17], v29 offset0:132 offset1:140
	ds_read2_b32 v[18:19], v29 offset0:165 offset1:173
	ds_read2_b32 v[20:21], v29 offset0:198 offset1:206
	ds_read2_b32 v[22:23], v29 offset0:231 offset1:239
	v_lshl_add_u64 v[4:5], s[14:15], 0, v[194:195]
	s_waitcnt lgkmcnt(6)
	v_cvt_pk_bf16_f32 v0, v8, v6
	s_waitcnt lgkmcnt(4)
	v_cvt_pk_bf16_f32 v1, v10, v14
	s_waitcnt lgkmcnt(2)
	v_cvt_pk_bf16_f32 v2, v16, v18
	s_waitcnt lgkmcnt(0)
	v_cvt_pk_bf16_f32 v3, v20, v22
	v_lshl_add_u64 v[24:25], v[4:5], 0, v[24:25]
	v_add_u32_e32 v6, s0, v26
	global_store_dwordx4 v[24:25], v[0:3], off nt
	v_add_u32_e32 v24, s0, v27
	v_ashrrev_i32_e32 v25, 31, v24
	v_cvt_pk_bf16_f32 v0, v9, v7
	v_ashrrev_i32_e32 v7, 31, v6
	v_lshlrev_b64 v[6:7], 9, v[6:7]
	v_cvt_pk_bf16_f32 v1, v11, v15
	v_cvt_pk_bf16_f32 v2, v17, v19
	v_cvt_pk_bf16_f32 v3, v21, v23
	v_lshl_add_u64 v[6:7], v[4:5], 0, v[6:7]
	global_store_dwordx4 v[6:7], v[0:3], off nt
	ds_read2_b32 v[6:7], v29 offset0:49 offset1:57
	ds_read2_b32 v[8:9], v29 offset0:16 offset1:24
	ds_read2_b32 v[10:11], v29 offset0:82 offset1:90
	ds_read2_b32 v[14:15], v29 offset0:115 offset1:123
	ds_read2_b32 v[16:17], v29 offset0:148 offset1:156
	ds_read2_b32 v[18:19], v29 offset0:181 offset1:189
	ds_read2_b32 v[20:21], v29 offset0:214 offset1:222
	ds_read2_b32 v[22:23], v29 offset0:247 offset1:255
	v_lshlrev_b64 v[24:25], 9, v[24:25]
	s_waitcnt lgkmcnt(6)
	v_cvt_pk_bf16_f32 v0, v8, v6
	s_waitcnt lgkmcnt(4)
	v_cvt_pk_bf16_f32 v1, v10, v14
	s_waitcnt lgkmcnt(2)
	v_cvt_pk_bf16_f32 v2, v16, v18
	s_waitcnt lgkmcnt(0)
	v_cvt_pk_bf16_f32 v3, v20, v22
	v_lshl_add_u64 v[24:25], v[4:5], 0, v[24:25]
	v_add_u32_e32 v6, s0, v28
	global_store_dwordx4 v[24:25], v[0:3], off nt
	s_nop 1
	v_cvt_pk_bf16_f32 v0, v9, v7
	v_ashrrev_i32_e32 v7, 31, v6
	v_lshlrev_b64 v[6:7], 9, v[6:7]
	v_cvt_pk_bf16_f32 v1, v11, v15
	v_cvt_pk_bf16_f32 v2, v17, v19
	v_cvt_pk_bf16_f32 v3, v21, v23
	v_lshl_add_u64 v[4:5], v[4:5], 0, v[6:7]
	global_store_dwordx4 v[4:5], v[0:3], off nt
	s_waitcnt lgkmcnt(0)

.LBB0_842:
	v_add_u32_e32 v4, 0x1ce0, v13
	s_waitcnt vmcnt(0)
	ds_write2_b32 v4, v0, v1 offset1:1
	v_add_u32_e32 v0, 0x1ce8, v13
	ds_write2_b32 v0, v2, v3 offset1:1
	v_lshlrev_b32_e32 v0, 3, v12
	v_and_b32_e32 v0, 56, v0
	v_mul_u32_u24_e32 v1, 0x84, v0
	v_lshlrev_b32_e32 v194, 1, v0
	v_lshlrev_b32_e32 v0, 2, v10
	s_waitcnt lgkmcnt(0)
	v_add3_u32 v13, s33, v1, v0
	ds_read2_b32 v[6:7], v13 offset0:33 offset1:41
	ds_read2_b32 v[16:17], v13 offset1:8
	ds_read2_b32 v[18:19], v13 offset0:66 offset1:74
	ds_read2_b32 v[20:21], v13 offset0:99 offset1:107
	ds_read2_b32 v[22:23], v13 offset0:132 offset1:140
	ds_read2_b32 v[24:25], v13 offset0:165 offset1:173
	ds_read2_b32 v[26:27], v13 offset0:198 offset1:206
	ds_read2_b32 v[28:29], v13 offset0:231 offset1:239
	s_lshl_b32 s0, s14, 1
	v_readlane_b32 s1, v255, 49
	s_add_u32 s0, s1, s0
	v_readlane_b32 s1, v255, 50
	v_add_u32_e32 v30, s3, v10
	s_addc_u32 s1, s1, 0
	v_ashrrev_i32_e32 v31, 31, v30
	v_lshl_add_u64 v[4:5], s[0:1], 0, v[194:195]
	v_lshlrev_b64 v[30:31], 11, v[30:31]
	s_waitcnt lgkmcnt(6)
	v_cvt_pk_bf16_f32 v0, v16, v6
	s_waitcnt lgkmcnt(4)
	v_cvt_pk_bf16_f32 v1, v18, v20
	s_waitcnt lgkmcnt(2)
	v_cvt_pk_bf16_f32 v2, v22, v24
	s_waitcnt lgkmcnt(0)
	v_cvt_pk_bf16_f32 v3, v26, v28
	v_lshl_add_u64 v[30:31], v[4:5], 0, v[30:31]
	v_add_u32_e32 v6, s3, v9
	global_store_dwordx4 v[30:31], v[0:3], off nt
	v_add_u32_e32 v10, s3, v11
	v_ashrrev_i32_e32 v11, 31, v10
	v_cvt_pk_bf16_f32 v0, v17, v7
	v_ashrrev_i32_e32 v7, 31, v6
	v_lshlrev_b64 v[6:7], 11, v[6:7]
	v_cvt_pk_bf16_f32 v1, v19, v21
	v_cvt_pk_bf16_f32 v2, v23, v25
	v_cvt_pk_bf16_f32 v3, v27, v29
	v_lshl_add_u64 v[6:7], v[4:5], 0, v[6:7]
	global_store_dwordx4 v[6:7], v[0:3], off nt
	ds_read2_b32 v[6:7], v13 offset0:49 offset1:57
	ds_read2_b32 v[8:9], v13 offset0:16 offset1:24
	ds_read2_b32 v[16:17], v13 offset0:82 offset1:90
	ds_read2_b32 v[18:19], v13 offset0:115 offset1:123
	ds_read2_b32 v[20:21], v13 offset0:148 offset1:156
	ds_read2_b32 v[22:23], v13 offset0:181 offset1:189
	ds_read2_b32 v[24:25], v13 offset0:214 offset1:222
	ds_read2_b32 v[26:27], v13 offset0:247 offset1:255
	v_lshlrev_b64 v[10:11], 11, v[10:11]
	s_waitcnt lgkmcnt(6)
	v_cvt_pk_bf16_f32 v0, v8, v6
	s_waitcnt lgkmcnt(4)
	v_cvt_pk_bf16_f32 v1, v16, v18
	s_waitcnt lgkmcnt(2)
	v_cvt_pk_bf16_f32 v2, v20, v22
	s_waitcnt lgkmcnt(0)
	v_cvt_pk_bf16_f32 v3, v24, v26
	v_lshl_add_u64 v[10:11], v[4:5], 0, v[10:11]
	v_add_u32_e32 v6, s3, v14
	global_store_dwordx4 v[10:11], v[0:3], off nt
	s_nop 1
	v_cvt_pk_bf16_f32 v0, v9, v7
	v_ashrrev_i32_e32 v7, 31, v6
	v_lshlrev_b64 v[6:7], 11, v[6:7]
	v_cvt_pk_bf16_f32 v1, v17, v19
	v_cvt_pk_bf16_f32 v2, v21, v23
	v_cvt_pk_bf16_f32 v3, v25, v27
	v_lshl_add_u64 v[4:5], v[4:5], 0, v[6:7]
	global_store_dwordx4 v[4:5], v[0:3], off nt
	s_waitcnt lgkmcnt(0)

.LBB0_844:
	s_andn2_b64 vcc, exec, s[0:1]
	s_cbranch_vccnz .LBB0_846
	s_add_i32 s0, s25, 0x1600
	s_and_b32 s1, s0, 0x1ffc0
	s_and_b32 s0, s55, 0x3e0
	v_ashrrev_i32_e32 v13, 3, v12
	s_lshl_b32 s3, s0, 2
	s_add_u32 s14, s92, s3
	v_lshlrev_b32_e32 v0, 4, v12
	v_add_u32_e32 v6, s1, v13
	s_addc_u32 s15, s96, 0
	v_and_b32_e32 v194, 0x70, v0
	v_ashrrev_i32_e32 v7, 31, v6
	v_lshl_add_u64 v[4:5], s[14:15], 0, v[194:195]
	v_lshlrev_b64 v[0:1], 12, v[6:7]
	v_lshl_add_u64 v[0:1], v[4:5], 0, v[0:1]
	global_load_dwordx4 v[0:3], v[0:1], off nt
	v_mul_lo_u32 v7, v13, s49
	v_add3_u32 v7, s33, v194, v7
	v_add_u32_e32 v26, 8, v13
	v_add_u32_e32 v8, 0x420, v7
	v_add_u32_e32 v27, 16, v13
	v_add_u32_e32 v28, 24, v13
	v_add_u32_e32 v24, s0, v13
	v_ashrrev_i32_e32 v25, 31, v24
	v_lshlrev_b64 v[24:25], 11, v[24:25]
	s_waitcnt vmcnt(0)
	ds_write2_b32 v7, v0, v1 offset1:1
	ds_write2_b32 v7, v2, v3 offset0:2 offset1:3
	v_add_u32_e32 v0, s1, v26
	v_ashrrev_i32_e32 v1, 31, v0
	v_lshlrev_b64 v[0:1], 12, v[0:1]
	v_lshl_add_u64 v[0:1], v[4:5], 0, v[0:1]
	global_load_dwordx4 v[0:3], v[0:1], off nt
	s_waitcnt vmcnt(0)
	ds_write2_b32 v8, v0, v1 offset1:1
	v_add_u32_e32 v0, 0x428, v7
	ds_write2_b32 v0, v2, v3 offset1:1
	v_add_u32_e32 v0, s1, v27
	v_ashrrev_i32_e32 v1, 31, v0
	v_lshlrev_b64 v[0:1], 12, v[0:1]
	v_lshl_add_u64 v[0:1], v[4:5], 0, v[0:1]
	global_load_dwordx4 v[0:3], v[0:1], off nt
	v_add_u32_e32 v8, 0x840, v7
	s_waitcnt vmcnt(0)
	ds_write2_b32 v8, v0, v1 offset1:1
	v_add_u32_e32 v0, 0x848, v7
	ds_write2_b32 v0, v2, v3 offset1:1
	v_add_u32_e32 v0, s1, v28
	v_ashrrev_i32_e32 v1, 31, v0
	v_lshlrev_b64 v[0:1], 12, v[0:1]
	v_lshl_add_u64 v[0:1], v[4:5], 0, v[0:1]
	global_load_dwordx4 v[0:3], v[0:1], off nt
	v_add_u32_e32 v8, 0xc60, v7
	s_lshl_b32 s1, s1, 1
	s_add_u32 s14, s30, s1
	s_addc_u32 s15, s31, 0
	s_waitcnt vmcnt(0)
	ds_write2_b32 v8, v0, v1 offset1:1
	v_add_u32_e32 v0, 0xc68, v7
	ds_write2_b32 v0, v2, v3 offset1:1
	v_add_u32_e32 v0, 32, v6
	v_ashrrev_i32_e32 v1, 31, v0
	v_lshlrev_b64 v[0:1], 12, v[0:1]
	v_lshl_add_u64 v[0:1], v[4:5], 0, v[0:1]
	global_load_dwordx4 v[0:3], v[0:1], off nt
	v_add_u32_e32 v8, 0x1080, v7
	s_waitcnt vmcnt(0)
	ds_write2_b32 v8, v0, v1 offset1:1
	v_add_u32_e32 v0, 0x1088, v7
	ds_write2_b32 v0, v2, v3 offset1:1
	v_add_u32_e32 v0, 40, v6
	v_ashrrev_i32_e32 v1, 31, v0
	v_lshlrev_b64 v[0:1], 12, v[0:1]
	v_lshl_add_u64 v[0:1], v[4:5], 0, v[0:1]
	global_load_dwordx4 v[0:3], v[0:1], off nt
	v_add_u32_e32 v8, 0x14a0, v7
	s_waitcnt vmcnt(0)
	ds_write2_b32 v8, v0, v1 offset1:1
	v_add_u32_e32 v0, 0x14a8, v7
	ds_write2_b32 v0, v2, v3 offset1:1
	v_add_u32_e32 v0, 48, v6
	v_ashrrev_i32_e32 v1, 31, v0
	v_lshlrev_b64 v[0:1], 12, v[0:1]
	v_lshl_add_u64 v[0:1], v[4:5], 0, v[0:1]
	global_load_dwordx4 v[0:3], v[0:1], off nt
	v_add_u32_e32 v8, 0x18c0, v7
	s_waitcnt vmcnt(0)
	ds_write2_b32 v8, v0, v1 offset1:1
	v_add_u32_e32 v0, 0x18c8, v7
	ds_write2_b32 v0, v2, v3 offset1:1
	v_add_u32_e32 v0, 56, v6
	v_ashrrev_i32_e32 v1, 31, v0
	v_lshlrev_b64 v[0:1], 12, v[0:1]
	v_lshl_add_u64 v[0:1], v[4:5], 0, v[0:1]
	global_load_dwordx4 v[0:3], v[0:1], off nt
	v_add_u32_e32 v4, 0x1ce0, v7
	s_waitcnt vmcnt(0)
	ds_write2_b32 v4, v0, v1 offset1:1
	v_add_u32_e32 v0, 0x1ce8, v7
	ds_write2_b32 v0, v2, v3 offset1:1
	v_lshlrev_b32_e32 v0, 3, v12
	v_and_b32_e32 v0, 56, v0
	v_mul_u32_u24_e32 v1, 0x84, v0
	v_lshlrev_b32_e32 v194, 1, v0
	v_lshlrev_b32_e32 v0, 2, v13
	s_waitcnt lgkmcnt(0)
	v_add3_u32 v29, s33, v1, v0
	ds_read2_b32 v[6:7], v29 offset0:33 offset1:41
	ds_read2_b32 v[8:9], v29 offset1:8
	ds_read2_b32 v[10:11], v29 offset0:66 offset1:74
	ds_read2_b32 v[14:15], v29 offset0:99 offset1:107
	ds_read2_b32 v[16:17], v29 offset0:132 offset1:140
	ds_read2_b32 v[18:19], v29 offset0:165 offset1:173
	ds_read2_b32 v[20:21], v29 offset0:198 offset1:206
	ds_read2_b32 v[22:23], v29 offset0:231 offset1:239
	v_lshl_add_u64 v[4:5], s[14:15], 0, v[194:195]
	s_waitcnt lgkmcnt(6)
	v_cvt_pk_bf16_f32 v0, v8, v6
	s_waitcnt lgkmcnt(4)
	v_cvt_pk_bf16_f32 v1, v10, v14
	s_waitcnt lgkmcnt(2)
	v_cvt_pk_bf16_f32 v2, v16, v18
	s_waitcnt lgkmcnt(0)
	v_cvt_pk_bf16_f32 v3, v20, v22
	v_lshl_add_u64 v[24:25], v[4:5], 0, v[24:25]
	v_add_u32_e32 v6, s0, v26
	global_store_dwordx4 v[24:25], v[0:3], off nt
	v_add_u32_e32 v24, s0, v27
	v_ashrrev_i32_e32 v25, 31, v24
	v_cvt_pk_bf16_f32 v0, v9, v7
	v_ashrrev_i32_e32 v7, 31, v6
	v_lshlrev_b64 v[6:7], 11, v[6:7]
	v_cvt_pk_bf16_f32 v1, v11, v15
	v_cvt_pk_bf16_f32 v2, v17, v19
	v_cvt_pk_bf16_f32 v3, v21, v23
	v_lshl_add_u64 v[6:7], v[4:5], 0, v[6:7]
	global_store_dwordx4 v[6:7], v[0:3], off nt
	ds_read2_b32 v[6:7], v29 offset0:49 offset1:57
	ds_read2_b32 v[8:9], v29 offset0:16 offset1:24
	ds_read2_b32 v[10:11], v29 offset0:82 offset1:90
	ds_read2_b32 v[14:15], v29 offset0:115 offset1:123
	ds_read2_b32 v[16:17], v29 offset0:148 offset1:156
	ds_read2_b32 v[18:19], v29 offset0:181 offset1:189
	ds_read2_b32 v[20:21], v29 offset0:214 offset1:222
	ds_read2_b32 v[22:23], v29 offset0:247 offset1:255
	v_lshlrev_b64 v[24:25], 11, v[24:25]
	s_waitcnt lgkmcnt(6)
	v_cvt_pk_bf16_f32 v0, v8, v6
	s_waitcnt lgkmcnt(4)
	v_cvt_pk_bf16_f32 v1, v10, v14
	s_waitcnt lgkmcnt(2)
	v_cvt_pk_bf16_f32 v2, v16, v18
	s_waitcnt lgkmcnt(0)
	v_cvt_pk_bf16_f32 v3, v20, v22
	v_lshl_add_u64 v[24:25], v[4:5], 0, v[24:25]
	v_add_u32_e32 v6, s0, v28
	global_store_dwordx4 v[24:25], v[0:3], off nt
	s_nop 1
	v_cvt_pk_bf16_f32 v0, v9, v7
	v_ashrrev_i32_e32 v7, 31, v6
	v_lshlrev_b64 v[6:7], 11, v[6:7]
	v_cvt_pk_bf16_f32 v1, v11, v15
	v_cvt_pk_bf16_f32 v2, v17, v19
	v_cvt_pk_bf16_f32 v3, v21, v23
	v_lshl_add_u64 v[4:5], v[4:5], 0, v[6:7]
	global_store_dwordx4 v[4:5], v[0:3], off nt
	s_waitcnt lgkmcnt(0)

.LBB0_847:
	s_andn2_b64 vcc, exec, s[0:1]
	s_cbranch_vccnz .LBB0_849
	s_add_i32 s0, s25, 0x1a00
	s_and_b32 s1, s0, 0x1ffc0
	s_and_b32 s0, s55, 0x3e0
	v_ashrrev_i32_e32 v13, 3, v12
	s_lshl_b32 s3, s0, 2
	s_add_u32 s14, s97, s3
	v_lshlrev_b32_e32 v0, 4, v12
	v_add_u32_e32 v6, s1, v13
	s_addc_u32 s15, s18, 0
	v_and_b32_e32 v194, 0x70, v0
	v_ashrrev_i32_e32 v7, 31, v6
	v_lshl_add_u64 v[4:5], s[14:15], 0, v[194:195]
	v_lshlrev_b64 v[0:1], 12, v[6:7]
	v_lshl_add_u64 v[0:1], v[4:5], 0, v[0:1]
	global_load_dwordx4 v[0:3], v[0:1], off nt
	v_mul_lo_u32 v7, v13, s49
	v_add3_u32 v7, s33, v194, v7
	v_add_u32_e32 v26, 8, v13
	v_add_u32_e32 v8, 0x420, v7
	v_add_u32_e32 v27, 16, v13
	v_add_u32_e32 v28, 24, v13
	v_add_u32_e32 v24, s0, v13
	v_ashrrev_i32_e32 v25, 31, v24
	v_lshlrev_b64 v[24:25], 11, v[24:25]
	s_waitcnt vmcnt(0)
	ds_write2_b32 v7, v0, v1 offset1:1
	ds_write2_b32 v7, v2, v3 offset0:2 offset1:3
	v_add_u32_e32 v0, s1, v26
	v_ashrrev_i32_e32 v1, 31, v0
	v_lshlrev_b64 v[0:1], 12, v[0:1]
	v_lshl_add_u64 v[0:1], v[4:5], 0, v[0:1]
	global_load_dwordx4 v[0:3], v[0:1], off nt
	s_waitcnt vmcnt(0)
	ds_write2_b32 v8, v0, v1 offset1:1
	v_add_u32_e32 v0, 0x428, v7
	ds_write2_b32 v0, v2, v3 offset1:1
	v_add_u32_e32 v0, s1, v27
	v_ashrrev_i32_e32 v1, 31, v0
	v_lshlrev_b64 v[0:1], 12, v[0:1]
	v_lshl_add_u64 v[0:1], v[4:5], 0, v[0:1]
	global_load_dwordx4 v[0:3], v[0:1], off nt
	v_add_u32_e32 v8, 0x840, v7
	s_waitcnt vmcnt(0)
	ds_write2_b32 v8, v0, v1 offset1:1
	v_add_u32_e32 v0, 0x848, v7
	ds_write2_b32 v0, v2, v3 offset1:1
	v_add_u32_e32 v0, s1, v28
	v_ashrrev_i32_e32 v1, 31, v0
	v_lshlrev_b64 v[0:1], 12, v[0:1]
	v_lshl_add_u64 v[0:1], v[4:5], 0, v[0:1]
	global_load_dwordx4 v[0:3], v[0:1], off nt
	v_add_u32_e32 v8, 0xc60, v7
	s_lshl_b32 s1, s1, 1
	s_add_u32 s14, s16, s1
	s_addc_u32 s15, s20, 0
	s_waitcnt vmcnt(0)
	ds_write2_b32 v8, v0, v1 offset1:1
	v_add_u32_e32 v0, 0xc68, v7
	ds_write2_b32 v0, v2, v3 offset1:1
	v_add_u32_e32 v0, 32, v6
	v_ashrrev_i32_e32 v1, 31, v0
	v_lshlrev_b64 v[0:1], 12, v[0:1]
	v_lshl_add_u64 v[0:1], v[4:5], 0, v[0:1]
	global_load_dwordx4 v[0:3], v[0:1], off nt
	v_add_u32_e32 v8, 0x1080, v7
	s_waitcnt vmcnt(0)
	ds_write2_b32 v8, v0, v1 offset1:1
	v_add_u32_e32 v0, 0x1088, v7
	ds_write2_b32 v0, v2, v3 offset1:1
	v_add_u32_e32 v0, 40, v6
	v_ashrrev_i32_e32 v1, 31, v0
	v_lshlrev_b64 v[0:1], 12, v[0:1]
	v_lshl_add_u64 v[0:1], v[4:5], 0, v[0:1]
	global_load_dwordx4 v[0:3], v[0:1], off nt
	v_add_u32_e32 v8, 0x14a0, v7
	s_waitcnt vmcnt(0)
	ds_write2_b32 v8, v0, v1 offset1:1
	v_add_u32_e32 v0, 0x14a8, v7
	ds_write2_b32 v0, v2, v3 offset1:1
	v_add_u32_e32 v0, 48, v6
	v_ashrrev_i32_e32 v1, 31, v0
	v_lshlrev_b64 v[0:1], 12, v[0:1]
	v_lshl_add_u64 v[0:1], v[4:5], 0, v[0:1]
	global_load_dwordx4 v[0:3], v[0:1], off nt
	v_add_u32_e32 v8, 0x18c0, v7
	s_waitcnt vmcnt(0)
	ds_write2_b32 v8, v0, v1 offset1:1
	v_add_u32_e32 v0, 0x18c8, v7
	ds_write2_b32 v0, v2, v3 offset1:1
	v_add_u32_e32 v0, 56, v6
	v_ashrrev_i32_e32 v1, 31, v0
	v_lshlrev_b64 v[0:1], 12, v[0:1]
	v_lshl_add_u64 v[0:1], v[4:5], 0, v[0:1]
	global_load_dwordx4 v[0:3], v[0:1], off nt
	v_add_u32_e32 v4, 0x1ce0, v7
	s_waitcnt vmcnt(0)
	ds_write2_b32 v4, v0, v1 offset1:1
	v_add_u32_e32 v0, 0x1ce8, v7
	ds_write2_b32 v0, v2, v3 offset1:1
	v_lshlrev_b32_e32 v0, 3, v12
	v_and_b32_e32 v0, 56, v0
	v_mul_u32_u24_e32 v1, 0x84, v0
	v_lshlrev_b32_e32 v194, 1, v0
	v_lshlrev_b32_e32 v0, 2, v13
	s_waitcnt lgkmcnt(0)
	v_add3_u32 v29, s33, v1, v0
	ds_read2_b32 v[6:7], v29 offset0:33 offset1:41
	ds_read2_b32 v[8:9], v29 offset1:8
	ds_read2_b32 v[10:11], v29 offset0:66 offset1:74
	ds_read2_b32 v[14:15], v29 offset0:99 offset1:107
	ds_read2_b32 v[16:17], v29 offset0:132 offset1:140
	ds_read2_b32 v[18:19], v29 offset0:165 offset1:173
	ds_read2_b32 v[20:21], v29 offset0:198 offset1:206
	ds_read2_b32 v[22:23], v29 offset0:231 offset1:239
	v_lshl_add_u64 v[4:5], s[14:15], 0, v[194:195]
	s_waitcnt lgkmcnt(6)
	v_cvt_pk_bf16_f32 v0, v8, v6
	s_waitcnt lgkmcnt(4)
	v_cvt_pk_bf16_f32 v1, v10, v14
	s_waitcnt lgkmcnt(2)
	v_cvt_pk_bf16_f32 v2, v16, v18
	s_waitcnt lgkmcnt(0)
	v_cvt_pk_bf16_f32 v3, v20, v22
	v_lshl_add_u64 v[24:25], v[4:5], 0, v[24:25]
	v_add_u32_e32 v6, s0, v26
	global_store_dwordx4 v[24:25], v[0:3], off nt
	v_add_u32_e32 v24, s0, v27
	v_ashrrev_i32_e32 v25, 31, v24
	v_cvt_pk_bf16_f32 v0, v9, v7
	v_ashrrev_i32_e32 v7, 31, v6
	v_lshlrev_b64 v[6:7], 11, v[6:7]
	v_cvt_pk_bf16_f32 v1, v11, v15
	v_cvt_pk_bf16_f32 v2, v17, v19
	v_cvt_pk_bf16_f32 v3, v21, v23
	v_lshl_add_u64 v[6:7], v[4:5], 0, v[6:7]
	global_store_dwordx4 v[6:7], v[0:3], off nt
	ds_read2_b32 v[6:7], v29 offset0:49 offset1:57
	ds_read2_b32 v[8:9], v29 offset0:16 offset1:24
	ds_read2_b32 v[10:11], v29 offset0:82 offset1:90
	ds_read2_b32 v[14:15], v29 offset0:115 offset1:123
	ds_read2_b32 v[16:17], v29 offset0:148 offset1:156
	ds_read2_b32 v[18:19], v29 offset0:181 offset1:189
	ds_read2_b32 v[20:21], v29 offset0:214 offset1:222
	ds_read2_b32 v[22:23], v29 offset0:247 offset1:255
	v_lshlrev_b64 v[24:25], 11, v[24:25]
	s_waitcnt lgkmcnt(6)
	v_cvt_pk_bf16_f32 v0, v8, v6
	s_waitcnt lgkmcnt(4)
	v_cvt_pk_bf16_f32 v1, v10, v14
	s_waitcnt lgkmcnt(2)
	v_cvt_pk_bf16_f32 v2, v16, v18
	s_waitcnt lgkmcnt(0)
	v_cvt_pk_bf16_f32 v3, v20, v22
	v_lshl_add_u64 v[24:25], v[4:5], 0, v[24:25]
	v_add_u32_e32 v6, s0, v28
	global_store_dwordx4 v[24:25], v[0:3], off nt
	s_nop 1
	v_cvt_pk_bf16_f32 v0, v9, v7
	v_ashrrev_i32_e32 v7, 31, v6
	v_lshlrev_b64 v[6:7], 11, v[6:7]
	v_cvt_pk_bf16_f32 v1, v11, v15
	v_cvt_pk_bf16_f32 v2, v17, v19
	v_cvt_pk_bf16_f32 v3, v21, v23
	v_lshl_add_u64 v[4:5], v[4:5], 0, v[6:7]
	global_store_dwordx4 v[4:5], v[0:3], off nt
	s_waitcnt lgkmcnt(0)

.LBB0_850:
	s_andn2_b64 vcc, exec, s[0:1]
	s_cbranch_vccnz .LBB0_852
	s_add_i32 s0, s25, 0x1e00
	s_and_b32 s1, s0, 0x1ffc0
	s_and_b32 s0, s55, 0x3e0
	v_ashrrev_i32_e32 v13, 3, v12
	s_lshl_b32 s3, s0, 2
	s_add_u32 s14, s19, s3
	v_lshlrev_b32_e32 v0, 4, v12
	v_add_u32_e32 v6, s1, v13
	s_addc_u32 s15, s22, 0
	v_and_b32_e32 v194, 0x70, v0
	v_ashrrev_i32_e32 v7, 31, v6
	v_lshl_add_u64 v[4:5], s[14:15], 0, v[194:195]
	v_lshlrev_b64 v[0:1], 12, v[6:7]
	v_lshl_add_u64 v[0:1], v[4:5], 0, v[0:1]
	global_load_dwordx4 v[0:3], v[0:1], off nt
	v_mul_lo_u32 v7, v13, s49
	v_add3_u32 v7, s33, v194, v7
	v_add_u32_e32 v26, 8, v13
	v_add_u32_e32 v8, 0x420, v7
	v_add_u32_e32 v27, 16, v13
	v_add_u32_e32 v28, 24, v13
	v_add_u32_e32 v24, s0, v13
	v_ashrrev_i32_e32 v25, 31, v24
	v_lshlrev_b64 v[24:25], 11, v[24:25]
	s_waitcnt vmcnt(0)
	ds_write2_b32 v7, v0, v1 offset1:1
	ds_write2_b32 v7, v2, v3 offset0:2 offset1:3
	v_add_u32_e32 v0, s1, v26
	v_ashrrev_i32_e32 v1, 31, v0
	v_lshlrev_b64 v[0:1], 12, v[0:1]
	v_lshl_add_u64 v[0:1], v[4:5], 0, v[0:1]
	global_load_dwordx4 v[0:3], v[0:1], off nt
	s_waitcnt vmcnt(0)
	ds_write2_b32 v8, v0, v1 offset1:1
	v_add_u32_e32 v0, 0x428, v7
	ds_write2_b32 v0, v2, v3 offset1:1
	v_add_u32_e32 v0, s1, v27
	v_ashrrev_i32_e32 v1, 31, v0
	v_lshlrev_b64 v[0:1], 12, v[0:1]
	v_lshl_add_u64 v[0:1], v[4:5], 0, v[0:1]
	global_load_dwordx4 v[0:3], v[0:1], off nt
	v_add_u32_e32 v8, 0x840, v7
	s_waitcnt vmcnt(0)
	ds_write2_b32 v8, v0, v1 offset1:1
	v_add_u32_e32 v0, 0x848, v7
	ds_write2_b32 v0, v2, v3 offset1:1
	v_add_u32_e32 v0, s1, v28
	v_ashrrev_i32_e32 v1, 31, v0
	v_lshlrev_b64 v[0:1], 12, v[0:1]
	v_lshl_add_u64 v[0:1], v[4:5], 0, v[0:1]
	global_load_dwordx4 v[0:3], v[0:1], off nt
	v_add_u32_e32 v8, 0xc60, v7
	s_lshl_b32 s1, s1, 1
	s_add_u32 s14, s35, s1
	s_addc_u32 s15, s26, 0
	s_waitcnt vmcnt(0)
	ds_write2_b32 v8, v0, v1 offset1:1
	v_add_u32_e32 v0, 0xc68, v7
	ds_write2_b32 v0, v2, v3 offset1:1
	v_add_u32_e32 v0, 32, v6
	v_ashrrev_i32_e32 v1, 31, v0
	v_lshlrev_b64 v[0:1], 12, v[0:1]
	v_lshl_add_u64 v[0:1], v[4:5], 0, v[0:1]
	global_load_dwordx4 v[0:3], v[0:1], off nt
	v_add_u32_e32 v8, 0x1080, v7
	s_waitcnt vmcnt(0)
	ds_write2_b32 v8, v0, v1 offset1:1
	v_add_u32_e32 v0, 0x1088, v7
	ds_write2_b32 v0, v2, v3 offset1:1
	v_add_u32_e32 v0, 40, v6
	v_ashrrev_i32_e32 v1, 31, v0
	v_lshlrev_b64 v[0:1], 12, v[0:1]
	v_lshl_add_u64 v[0:1], v[4:5], 0, v[0:1]
	global_load_dwordx4 v[0:3], v[0:1], off nt
	v_add_u32_e32 v8, 0x14a0, v7
	s_waitcnt vmcnt(0)
	ds_write2_b32 v8, v0, v1 offset1:1
	v_add_u32_e32 v0, 0x14a8, v7
	ds_write2_b32 v0, v2, v3 offset1:1
	v_add_u32_e32 v0, 48, v6
	v_ashrrev_i32_e32 v1, 31, v0
	v_lshlrev_b64 v[0:1], 12, v[0:1]
	v_lshl_add_u64 v[0:1], v[4:5], 0, v[0:1]
	global_load_dwordx4 v[0:3], v[0:1], off nt
	v_add_u32_e32 v8, 0x18c0, v7
	s_waitcnt vmcnt(0)
	ds_write2_b32 v8, v0, v1 offset1:1
	v_add_u32_e32 v0, 0x18c8, v7
	ds_write2_b32 v0, v2, v3 offset1:1
	v_add_u32_e32 v0, 56, v6
	v_ashrrev_i32_e32 v1, 31, v0
	v_lshlrev_b64 v[0:1], 12, v[0:1]
	v_lshl_add_u64 v[0:1], v[4:5], 0, v[0:1]
	global_load_dwordx4 v[0:3], v[0:1], off nt
	v_add_u32_e32 v4, 0x1ce0, v7
	s_waitcnt vmcnt(0)
	ds_write2_b32 v4, v0, v1 offset1:1
	v_add_u32_e32 v0, 0x1ce8, v7
	ds_write2_b32 v0, v2, v3 offset1:1
	v_lshlrev_b32_e32 v0, 3, v12
	v_and_b32_e32 v0, 56, v0
	v_mul_u32_u24_e32 v1, 0x84, v0
	v_lshlrev_b32_e32 v194, 1, v0
	v_lshlrev_b32_e32 v0, 2, v13
	s_waitcnt lgkmcnt(0)
	v_add3_u32 v29, s33, v1, v0
	ds_read2_b32 v[6:7], v29 offset0:33 offset1:41
	ds_read2_b32 v[8:9], v29 offset1:8
	ds_read2_b32 v[10:11], v29 offset0:66 offset1:74
	ds_read2_b32 v[14:15], v29 offset0:99 offset1:107
	ds_read2_b32 v[16:17], v29 offset0:132 offset1:140
	ds_read2_b32 v[18:19], v29 offset0:165 offset1:173
	ds_read2_b32 v[20:21], v29 offset0:198 offset1:206
	ds_read2_b32 v[22:23], v29 offset0:231 offset1:239
	v_lshl_add_u64 v[4:5], s[14:15], 0, v[194:195]
	s_waitcnt lgkmcnt(6)
	v_cvt_pk_bf16_f32 v0, v8, v6
	s_waitcnt lgkmcnt(4)
	v_cvt_pk_bf16_f32 v1, v10, v14
	s_waitcnt lgkmcnt(2)
	v_cvt_pk_bf16_f32 v2, v16, v18
	s_waitcnt lgkmcnt(0)
	v_cvt_pk_bf16_f32 v3, v20, v22
	v_lshl_add_u64 v[24:25], v[4:5], 0, v[24:25]
	v_add_u32_e32 v6, s0, v26
	global_store_dwordx4 v[24:25], v[0:3], off nt
	v_add_u32_e32 v24, s0, v27
	v_ashrrev_i32_e32 v25, 31, v24
	v_cvt_pk_bf16_f32 v0, v9, v7
	v_ashrrev_i32_e32 v7, 31, v6
	v_lshlrev_b64 v[6:7], 11, v[6:7]
	v_cvt_pk_bf16_f32 v1, v11, v15
	v_cvt_pk_bf16_f32 v2, v17, v19
	v_cvt_pk_bf16_f32 v3, v21, v23
	v_lshl_add_u64 v[6:7], v[4:5], 0, v[6:7]
	global_store_dwordx4 v[6:7], v[0:3], off nt
	ds_read2_b32 v[6:7], v29 offset0:49 offset1:57
	ds_read2_b32 v[8:9], v29 offset0:16 offset1:24
	ds_read2_b32 v[10:11], v29 offset0:82 offset1:90
	ds_read2_b32 v[14:15], v29 offset0:115 offset1:123
	ds_read2_b32 v[16:17], v29 offset0:148 offset1:156
	ds_read2_b32 v[18:19], v29 offset0:181 offset1:189
	ds_read2_b32 v[20:21], v29 offset0:214 offset1:222
	ds_read2_b32 v[22:23], v29 offset0:247 offset1:255
	v_lshlrev_b64 v[24:25], 11, v[24:25]
	s_waitcnt lgkmcnt(6)
	v_cvt_pk_bf16_f32 v0, v8, v6
	s_waitcnt lgkmcnt(4)
	v_cvt_pk_bf16_f32 v1, v10, v14
	s_waitcnt lgkmcnt(2)
	v_cvt_pk_bf16_f32 v2, v16, v18
	s_waitcnt lgkmcnt(0)
	v_cvt_pk_bf16_f32 v3, v20, v22
	v_lshl_add_u64 v[24:25], v[4:5], 0, v[24:25]
	v_add_u32_e32 v6, s0, v28
	global_store_dwordx4 v[24:25], v[0:3], off nt
	s_nop 1
	v_cvt_pk_bf16_f32 v0, v9, v7
	v_ashrrev_i32_e32 v7, 31, v6
	v_lshlrev_b64 v[6:7], 11, v[6:7]
	v_cvt_pk_bf16_f32 v1, v11, v15
	v_cvt_pk_bf16_f32 v2, v17, v19
	v_cvt_pk_bf16_f32 v3, v21, v23
	v_lshl_add_u64 v[4:5], v[4:5], 0, v[6:7]
	global_store_dwordx4 v[4:5], v[0:3], off nt
	s_waitcnt lgkmcnt(0)

.LBB0_968:
	s_and_b32 s30, s3, 3
	v_lshlrev_b32_e32 v2, 3, v8
	v_and_b32_e32 v5, 56, v2
	v_ashrrev_i32_e32 v2, 3, v8
	s_lshl_b32 s3, s30, 6
	s_mov_b64 s[4:5], -1
	s_and_b64 vcc, exec, s[22:23]
	s_cbranch_vccz .LBB0_970
	v_ashrrev_i32_e32 v3, 31, v2
	v_lshlrev_b64 v[10:11], 8, v[2:3]
	s_ashr_i32 s19, s18, 31
	v_lshl_add_u64 v[10:11], v[10:11], 0, s[10:11]
	s_lshl_b64 s[4:5], s[18:19], 16
	v_or_b32_e32 v10, v10, v5
	v_lshl_add_u64 v[10:11], v[10:11], 0, s[4:5]
	v_or_b32_e32 v10, s3, v10
	v_readlane_b32 s56, v253, 42
	v_lshlrev_b64 v[18:19], 2, v[10:11]
	v_readlane_b32 s68, v253, 54
	v_readlane_b32 s69, v253, 55
	v_readlane_b32 s70, v253, 56
	v_readlane_b32 s71, v253, 57
	v_lshl_add_u64 v[14:15], s[68:69], 0, v[18:19]
	global_load_dwordx4 v[20:23], v[14:15], off offset:16 nt
	global_load_dwordx4 v[24:27], v[14:15], off nt
	v_readlane_b32 s64, v253, 50
	v_readlane_b32 s66, v253, 52
	v_readlane_b32 s57, v253, 43
	v_readlane_b32 s58, v253, 44
	v_readlane_b32 s59, v253, 45
	v_readlane_b32 s60, v253, 46
	v_readlane_b32 s61, v253, 47
	v_readlane_b32 s62, v253, 48
	v_readlane_b32 s63, v253, 49
	v_readlane_b32 s65, v253, 51
	v_readlane_b32 s67, v253, 53
	s_mov_b32 s66, 0x3a800000
	s_mov_b32 s64, s90
	s_mov_b64 s[4:5], 0
	v_lshl_add_u64 v[14:15], s[70:71], 0, v[18:19]
	global_load_dwordx4 v[28:31], v[14:15], off offset:16 nt
	global_load_dwordx4 v[32:35], v[14:15], off nt
	s_mov_b64 s[70:71], s[84:85]

.LBB0_972:
	v_add_u32_e32 v2, 0x200, v8
	v_ashrrev_i32_e32 v4, 3, v2
	v_cndmask_b32_e64 v2, 0, 1, s[22:23]
	s_mov_b64 s[24:25], -1
	v_cmp_ne_u32_e64 s[4:5], 1, v2
	s_andn2_b64 vcc, exec, s[22:23]
	v_or_b32_e32 v2, s10, v5
	s_cbranch_vccnz .LBB0_974
	v_ashrrev_i32_e32 v5, 31, v4
	s_ashr_i32 s19, s18, 31
	v_lshlrev_b64 v[10:11], 8, v[4:5]
	v_mov_b32_e32 v3, v195
	s_lshl_b64 s[22:23], s[18:19], 16
	v_lshl_add_u64 v[10:11], v[2:3], 0, v[10:11]
	v_lshl_add_u64 v[10:11], v[10:11], 0, s[22:23]
	v_or_b32_e32 v10, s3, v10
	v_readlane_b32 s56, v253, 42
	v_lshlrev_b64 v[18:19], 2, v[10:11]
	v_readlane_b32 s68, v253, 54
	v_readlane_b32 s69, v253, 55
	v_readlane_b32 s70, v253, 56
	v_readlane_b32 s71, v253, 57
	v_lshl_add_u64 v[14:15], s[68:69], 0, v[18:19]
	global_load_dwordx4 v[36:39], v[14:15], off offset:16 nt
	global_load_dwordx4 v[40:43], v[14:15], off nt
	v_readlane_b32 s64, v253, 50
	v_readlane_b32 s66, v253, 52
	s_mov_b32 s66, 0x3a800000
	s_mov_b32 s64, s90
	s_mov_b64 s[24:25], 0
	v_readlane_b32 s57, v253, 43
	v_readlane_b32 s58, v253, 44
	v_readlane_b32 s59, v253, 45
	v_readlane_b32 s60, v253, 46
	v_readlane_b32 s61, v253, 47
	v_readlane_b32 s62, v253, 48
	v_readlane_b32 s63, v253, 49
	v_readlane_b32 s65, v253, 51
	v_readlane_b32 s67, v253, 53
	v_lshl_add_u64 v[14:15], s[70:71], 0, v[18:19]
	global_load_dwordx4 v[44:47], v[14:15], off offset:16 nt
	global_load_dwordx4 v[48:51], v[14:15], off nt
	s_mov_b64 s[70:71], s[84:85]

.LBB0_976:
	v_add_u32_e32 v3, 0x400, v8
	v_ashrrev_i32_e32 v4, 3, v3
	s_and_b64 vcc, exec, s[4:5]
	s_mov_b64 s[22:23], -1
	s_cbranch_vccnz .LBB0_978
	v_ashrrev_i32_e32 v5, 31, v4
	s_ashr_i32 s19, s18, 31
	v_lshlrev_b64 v[10:11], 8, v[4:5]
	v_mov_b32_e32 v3, v195
	s_lshl_b64 s[22:23], s[18:19], 16
	v_lshl_add_u64 v[10:11], v[2:3], 0, v[10:11]
	v_lshl_add_u64 v[10:11], v[10:11], 0, s[22:23]
	v_or_b32_e32 v10, s3, v10
	v_readlane_b32 s56, v253, 42
	v_lshlrev_b64 v[18:19], 2, v[10:11]
	v_readlane_b32 s68, v253, 54
	v_readlane_b32 s69, v253, 55
	v_readlane_b32 s70, v253, 56
	v_readlane_b32 s71, v253, 57
	v_lshl_add_u64 v[14:15], s[68:69], 0, v[18:19]
	global_load_dwordx4 v[52:55], v[14:15], off offset:16 nt
	global_load_dwordx4 v[56:59], v[14:15], off nt
	v_readlane_b32 s64, v253, 50
	v_readlane_b32 s66, v253, 52
	s_mov_b32 s66, 0x3a800000
	s_mov_b32 s64, s90
	s_mov_b64 s[22:23], 0
	v_readlane_b32 s57, v253, 43
	v_readlane_b32 s58, v253, 44
	v_readlane_b32 s59, v253, 45
	v_readlane_b32 s60, v253, 46
	v_readlane_b32 s61, v253, 47
	v_readlane_b32 s62, v253, 48
	v_readlane_b32 s63, v253, 49
	v_readlane_b32 s65, v253, 51
	v_readlane_b32 s67, v253, 53
	v_lshl_add_u64 v[14:15], s[70:71], 0, v[18:19]
	global_load_dwordx4 v[60:63], v[14:15], off offset:16 nt
	global_load_dwordx4 v[64:67], v[14:15], off nt
	s_mov_b64 s[70:71], s[84:85]

.LBB0_980:
	v_add_u32_e32 v3, 0x600, v8
	v_ashrrev_i32_e32 v4, 3, v3
	s_and_b64 vcc, exec, s[4:5]
	s_mov_b64 s[4:5], -1
	s_cbranch_vccnz .LBB0_982
	v_ashrrev_i32_e32 v5, 31, v4
	s_ashr_i32 s19, s18, 31
	v_lshlrev_b64 v[8:9], 8, v[4:5]
	v_mov_b32_e32 v3, v195
	s_lshl_b64 s[4:5], s[18:19], 16
	v_lshl_add_u64 v[2:3], v[2:3], 0, v[8:9]
	v_lshl_add_u64 v[2:3], v[2:3], 0, s[4:5]
	v_or_b32_e32 v2, s3, v2
	v_readlane_b32 s56, v253, 42
	v_lshlrev_b64 v[2:3], 2, v[2:3]
	v_readlane_b32 s68, v253, 54
	v_readlane_b32 s69, v253, 55
	v_readlane_b32 s70, v253, 56
	v_readlane_b32 s71, v253, 57
	v_lshl_add_u64 v[12:13], s[68:69], 0, v[2:3]
	global_load_dwordx4 v[68:71], v[12:13], off offset:16 nt
	global_load_dwordx4 v[72:75], v[12:13], off nt
	v_lshl_add_u64 v[2:3], s[70:71], 0, v[2:3]
	v_readlane_b32 s64, v253, 50
	v_readlane_b32 s66, v253, 52
	s_mov_b32 s66, 0x3a800000
	s_mov_b32 s64, s90
	s_mov_b64 s[70:71], s[84:85]
	s_mov_b64 s[4:5], 0
	v_readlane_b32 s57, v253, 43
	v_readlane_b32 s58, v253, 44
	v_readlane_b32 s59, v253, 45
	v_readlane_b32 s60, v253, 46
	v_readlane_b32 s61, v253, 47
	v_readlane_b32 s62, v253, 48
	v_readlane_b32 s63, v253, 49
	v_readlane_b32 s65, v253, 51
	v_readlane_b32 s67, v253, 53
	global_load_dwordx4 v[76:79], v[2:3], off offset:16 nt
	global_load_dwordx4 v[80:83], v[2:3], off nt
